# comb10 + attention softmax: s-m subtractions and pairwise row-sum adds issued as v_pk_add_f32 (same ops per element, 24 fewer VALU per tile per wave)
# baseline (speedup 1.0000x reference)
; #define LAS __attribute__((address_space(3)))
; __device__ __forceinline__ unsigned cvt_pk(float lo, float hi) { unsigned r; asm volatile("v_cvt_pk_bf16_f32 %0, %1, %2" : "=v"(r) : "v"(lo), "v"(hi)); return r; }
; __device__ __forceinline__ void attn_unit(LAS unsigned char* lds, int b, int h, int q0, int kbeg, int ntiles, const bf16_t* Q, const bf16_t* K, const bf16_t* Vt, bf16_t* cat) {
;     ...
;         const LAS unsigned char* kb = lds + (buf ^ 1) * AK_BYTES + r32 * (KP * 2) + hi * 16;
;         f32x16 pn0, pn1;
; #pragma unroll
;         for (int r = 0; r < 16; ++r) { pn0[r] = 0.f; pn1[r] = 0.f; }
;         float ps = 0.f; u32x4 pw[4];
;         bf16x8 ka = *(const LAS bf16x8*)(kb), kbb = *(const LAS bf16x8*)(kb + 32 * (KP * 2));
; #pragma unroll
;         for (int ds = 0; ds < 12; ++ds) {
;             bf16x8 na = ka, nb = kbb;
;             if (ds < 11) { na = *(const LAS bf16x8*)(kb + (ds + 1) * 32); nb = *(const LAS bf16x8*)(kb + 32 * (KP * 2) + (ds + 1) * 32); }
;             pn0 = __builtin_amdgcn_mfma_f32_32x32x16_bf16(ka, qf[ds], pn0, 0, 0, 0);
;             pn1 = __builtin_amdgcn_mfma_f32_32x32x16_bf16(kbb, qf[ds], pn1, 0, 0, 0);
;             if (ds < 8) {
;                 float e[4];
; #pragma unroll
;                 for (int j = 0; j < 4; ++j) { const float v = ds < 4 ? pc0[4 * ds + j] : pc1[4 * (ds - 4) + j]; e[j] = __builtin_amdgcn_exp2f(v - mrun); }
;                 ps += (e[0] + e[1]) + (e[2] + e[3]);
;                 const unsigned w0 = cvt_pk(e[0], e[1]), w1 = cvt_pk(e[2], e[3]);
;                 if ((ds & 1) == 0) { pw[ds >> 1].x = w0; pw[ds >> 1].y = w1; } else { pw[ds >> 1].z = w0; pw[ds >> 1].w = w1; }
;             }
;             ka = na; kbb = nb;
;             __builtin_amdgcn_sched_barrier(0);
;         }
.LBB0_814:
	s_xor_b32 s6, s5, 1
	s_mul_i32 s7, s6, 0x6400
	v_add_u32_e32 v236, s7, v228
	ds_read_b128 v[98:101], v236
	v_pk_add_f32 v[82:83], v[82:83], v[230:231] op_sel:[0,0] op_sel_hi:[1,0] neg_lo:[0,1] neg_hi:[0,1]
	v_exp_f32_e32 v197, v82
	v_pk_add_f32 v[84:85], v[84:85], v[230:231] op_sel:[0,0] op_sel_hi:[1,0] neg_lo:[0,1] neg_hi:[0,1]
	v_exp_f32_e32 v201, v84
	v_exp_f32_e32 v233, v85
	v_pk_add_f32 v[86:87], v[86:87], v[230:231] op_sel:[0,0] op_sel_hi:[1,0] neg_lo:[0,1] neg_hi:[0,1]
	v_exp_f32_e32 v196, v86
	s_waitcnt lgkmcnt(0)
	v_mfma_f32_32x32x16_bf16 v[98:113], v[98:101], v[174:177], 0
	v_exp_f32_e32 v198, v87
	v_pk_add_f32 v[88:89], v[88:89], v[230:231] op_sel:[0,0] op_sel_hi:[1,0] neg_lo:[0,1] neg_hi:[0,1]
	v_exp_f32_e32 v200, v88
	v_exp_f32_e32 v199, v83
	v_exp_f32_e32 v232, v89
	ds_read_b128 v[188:191], v236 offset:32
	ds_read_b128 v[114:117], v236 offset:12800
	ds_read_b128 v[192:195], v236 offset:12832
	s_add_i32 s4, s4, 1
	v_pk_add_f32 v[82:83], v[196:197], v[198:199]
	v_pk_add_f32 v[84:85], v[200:201], v[232:233]
	s_waitcnt lgkmcnt(0)
	v_mfma_f32_32x32x16_bf16 v[114:129], v[114:117], v[174:177], 0
	v_pk_add_f32 v[234:235], v[82:83], v[84:85] op_sel:[0,0] op_sel_hi:[1,1]
	v_cvt_pk_bf16_f32 v186, v197, v199
	v_cvt_pk_bf16_f32 v187, v201, v233
	v_add_f32_e32 v235, 0, v235
	v_mfma_f32_32x32x16_bf16 v[98:113], v[188:191], v[170:173], v[98:113]
	ds_read_b128 v[82:85], v236 offset:64
	ds_read_b128 v[86:89], v236 offset:12864
	v_add_f32_e32 v197, v234, v235
	v_cvt_pk_bf16_f32 v188, v196, v198
	v_cvt_pk_bf16_f32 v189, v200, v232
	v_mfma_f32_32x32x16_bf16 v[114:129], v[192:195], v[170:173], v[114:129]
	v_pk_add_f32 v[90:91], v[90:91], v[230:231] op_sel:[0,0] op_sel_hi:[1,0] neg_lo:[0,1] neg_hi:[0,1]
	s_waitcnt lgkmcnt(0)
	v_mfma_f32_32x32x16_bf16 v[98:113], v[82:85], v[166:169], v[98:113]
	v_exp_f32_e32 v190, v90
	v_exp_f32_e32 v192, v91
	v_pk_add_f32 v[92:93], v[92:93], v[230:231] op_sel:[0,0] op_sel_hi:[1,0] neg_lo:[0,1] neg_hi:[0,1]
	v_exp_f32_e32 v191, v92
	v_exp_f32_e32 v193, v93
	ds_read_b128 v[82:85], v236 offset:96
	ds_read_b128 v[90:93], v236 offset:12896
	v_mfma_f32_32x32x16_bf16 v[114:129], v[86:89], v[166:169], v[114:129]
	v_pk_add_f32 v[194:195], v[190:191], v[192:193] op_sel:[0,0] op_sel_hi:[1,1]
	v_pk_add_f32 v[198:199], v[194:195], v[194:195] op_sel:[0,0] op_sel_hi:[0,1]
	v_cvt_pk_bf16_f32 v190, v190, v192
	v_cvt_pk_bf16_f32 v191, v191, v193
	v_pk_add_f32 v[94:95], v[94:95], v[230:231] op_sel:[0,0] op_sel_hi:[1,0] neg_lo:[0,1] neg_hi:[0,1]
	s_waitcnt lgkmcnt(0)
	v_mfma_f32_32x32x16_bf16 v[98:113], v[82:85], v[162:165], v[98:113]
	v_exp_f32_e32 v94, v94
	v_exp_f32_e32 v192, v95
	v_pk_add_f32 v[96:97], v[96:97], v[230:231] op_sel:[0,0] op_sel_hi:[1,0] neg_lo:[0,1] neg_hi:[0,1]
	v_exp_f32_e32 v96, v96
	v_exp_f32_e32 v193, v97
	ds_read_b128 v[82:85], v236 offset:128
	ds_read_b128 v[86:89], v236 offset:12928
	v_add_f32_e32 v95, v94, v192
	v_cvt_pk_bf16_f32 v192, v94, v192
	v_add_f32_e32 v97, v96, v193
	v_mfma_f32_32x32x16_bf16 v[114:129], v[90:93], v[162:165], v[114:129]
	v_cvt_pk_bf16_f32 v193, v96, v193
	v_pk_add_f32 v[66:67], v[66:67], v[230:231] op_sel:[0,0] op_sel_hi:[1,0] neg_lo:[0,1] neg_hi:[0,1]
	v_exp_f32_e32 v94, v66
	v_exp_f32_e32 v96, v67
	v_pk_add_f32 v[68:69], v[68:69], v[230:231] op_sel:[0,0] op_sel_hi:[1,0] neg_lo:[0,1] neg_hi:[0,1]
	v_exp_f32_e32 v198, v68
	s_waitcnt lgkmcnt(0)
	v_mfma_f32_32x32x16_bf16 v[98:113], v[82:85], v[158:161], v[98:113]
	v_exp_f32_e32 v196, v69
	ds_read_b128 v[66:69], v236 offset:160
	ds_read_b128 v[82:85], v236 offset:12960
	v_pk_add_f32 v[90:91], v[94:95], v[96:97]
	v_cvt_pk_bf16_f32 v194, v94, v96
	v_pk_add_f32 v[92:93], v[198:199], v[196:197]
	v_cvt_pk_bf16_f32 v195, v198, v196
	v_mfma_f32_32x32x16_bf16 v[114:129], v[86:89], v[158:161], v[114:129]
	v_pk_add_f32 v[90:91], v[90:91], v[92:93] op_sel:[0,0] op_sel_hi:[1,1]
	v_pk_add_f32 v[86:87], v[90:91], v[90:91] op_sel:[0,0] op_sel_hi:[0,1]
	v_pk_add_f32 v[70:71], v[70:71], v[230:231] op_sel:[0,0] op_sel_hi:[1,0] neg_lo:[0,1] neg_hi:[0,1]
	v_exp_f32_e32 v88, v70
	s_waitcnt lgkmcnt(0)
	v_mfma_f32_32x32x16_bf16 v[98:113], v[66:69], v[154:157], v[98:113]
	v_exp_f32_e32 v90, v71
	v_pk_add_f32 v[72:73], v[72:73], v[230:231] op_sel:[0,0] op_sel_hi:[1,0] neg_lo:[0,1] neg_hi:[0,1]
	v_exp_f32_e32 v89, v72
	v_exp_f32_e32 v91, v73
	ds_read_b128 v[66:69], v236 offset:192
	ds_read_b128 v[70:73], v236 offset:12992
	v_cvt_pk_bf16_f32 v196, v88, v90
	v_mfma_f32_32x32x16_bf16 v[114:129], v[82:85], v[154:157], v[114:129]
	v_pk_add_f32 v[92:93], v[88:89], v[90:91] op_sel:[0,0] op_sel_hi:[1,1]
	v_cvt_pk_bf16_f32 v197, v89, v91
	v_pk_add_f32 v[92:93], v[92:93], v[92:93] op_sel_hi:[0,1]
	v_pk_add_f32 v[74:75], v[74:75], v[230:231] op_sel:[0,0] op_sel_hi:[1,0] neg_lo:[0,1] neg_hi:[0,1]
	s_waitcnt lgkmcnt(0)
	v_mfma_f32_32x32x16_bf16 v[98:113], v[66:69], v[150:153], v[98:113]
	v_exp_f32_e32 v82, v74
	v_exp_f32_e32 v84, v75
	v_pk_add_f32 v[76:77], v[76:77], v[230:231] op_sel:[0,0] op_sel_hi:[1,0] neg_lo:[0,1] neg_hi:[0,1]
	v_exp_f32_e32 v86, v76
	v_exp_f32_e32 v88, v77
	ds_read_b128 v[66:69], v236 offset:224
	ds_read_b128 v[74:77], v236 offset:13024
	v_add_f32_e32 v83, v82, v84
	v_cvt_pk_bf16_f32 v198, v82, v84
	v_add_f32_e32 v85, v86, v88
	v_mfma_f32_32x32x16_bf16 v[114:129], v[70:73], v[150:153], v[114:129]
	v_cvt_pk_bf16_f32 v199, v86, v88
	v_pk_add_f32 v[78:79], v[78:79], v[230:231] op_sel:[0,0] op_sel_hi:[1,0] neg_lo:[0,1] neg_hi:[0,1]
	v_exp_f32_e32 v82, v78
	s_waitcnt lgkmcnt(0)
; #define LAS __attribute__((address_space(3)))
; __device__ __forceinline__ unsigned cvt_pk(float lo, float hi) { unsigned r; asm volatile("v_cvt_pk_bf16_f32 %0, %1, %2" : "=v"(r) : "v"(lo), "v"(hi)); return r; }
; __device__ __forceinline__ void attn_unit(LAS unsigned char* lds, int b, int h, int q0, int kbeg, int ntiles, const bf16_t* Q, const bf16_t* K, const bf16_t* Vt, bf16_t* cat) {
;     ...
;         for (int ds = 0; ds < 12; ++ds) {
;             bf16x8 na = ka, nb = kbb;
;             if (ds < 11) { na = *(const LAS bf16x8*)(kb + (ds + 1) * 32); nb = *(const LAS bf16x8*)(kb + 32 * (KP * 2) + (ds + 1) * 32); }
;             pn0 = __builtin_amdgcn_mfma_f32_32x32x16_bf16(ka, qf[ds], pn0, 0, 0, 0);
;             pn1 = __builtin_amdgcn_mfma_f32_32x32x16_bf16(kbb, qf[ds], pn1, 0, 0, 0);
;             if (ds < 8) {
;                 float e[4];
; #pragma unroll
;                 for (int j = 0; j < 4; ++j) { const float v = ds < 4 ? pc0[4 * ds + j] : pc1[4 * (ds - 4) + j]; e[j] = __builtin_amdgcn_exp2f(v - mrun); }
;                 ps += (e[0] + e[1]) + (e[2] + e[3]);
;                 const unsigned w0 = cvt_pk(e[0], e[1]), w1 = cvt_pk(e[2], e[3]);
;                 if ((ds & 1) == 0) { pw[ds >> 1].x = w0; pw[ds >> 1].y = w1; } else { pw[ds >> 1].z = w0; pw[ds >> 1].w = w1; }
;             }
;             ka = na; kbb = nb;
;             __builtin_amdgcn_sched_barrier(0);
;         }
;         lrun += ps;
;         const LAS unsigned char* vb = lds + 2 * AK_BYTES + buf * AV_BYTES + r32 * AV_PITCH + hi * 8;
; #pragma unroll
;         for (int d = 0; d < 4; ++d)
; #pragma unroll
;             for (int ks = 0; ks < 4; ++ks) {
;                 const s16x4 lo = *(const LAS s16x4*)(vb + d * 32 * AV_PITCH + ks * 32), hh = *(const LAS s16x4*)(vb + d * 32 * AV_PITCH + ks * 32 + 16);
;                 const bf16x8 vf = (bf16x8){lo[0], lo[1], lo[2], lo[3], hh[0], hh[1], hh[2], hh[3]};
;                 o[d] = __builtin_amdgcn_mfma_f32_32x32x16_bf16(vf, __builtin_bit_cast(bf16x8, pw[ks]), o[d], 0, 0, 0);
;             }
;         { float mx = fmaxf(pn0[0], pn1[0]);
; #pragma unroll
;           for (int r = 1; r < 16; ++r) mx = fmaxf(mx, fmaxf(pn0[r], pn1[r]));
;           mxc = fmaxf(mx, __shfl_xor(mx, 32)); }
;         if (kt + 1 < ntiles) ASTOREV(buf ^ 1);
;         asm volatile("s_waitcnt vmcnt(0)" ::: "memory");
;         __syncthreads();
	v_mfma_f32_32x32x16_bf16 v[98:113], v[66:69], v[146:149], v[98:113]
	v_exp_f32_e32 v84, v79
	v_pk_add_f32 v[80:81], v[80:81], v[230:231] op_sel:[0,0] op_sel_hi:[1,0] neg_lo:[0,1] neg_hi:[0,1]
	v_exp_f32_e32 v92, v80
	v_exp_f32_e32 v86, v81
	ds_read_b128 v[66:69], v236 offset:256
	ds_read_b128 v[70:73], v236 offset:13056
	v_pk_add_f32 v[78:79], v[82:83], v[84:85]
	v_mfma_f32_32x32x16_bf16 v[114:129], v[74:77], v[146:149], v[114:129]
	v_pk_add_f32 v[80:81], v[92:93], v[86:87] op_sel:[0,0] op_sel_hi:[1,1]
	v_cvt_pk_bf16_f32 v200, v82, v84
	v_cvt_pk_bf16_f32 v201, v92, v86
	v_pk_add_f32 v[78:79], v[78:79], v[80:81] op_sel:[0,0] op_sel_hi:[1,1]
	v_add_f32_e32 v237, v78, v79
	s_waitcnt lgkmcnt(0)
	v_mfma_f32_32x32x16_bf16 v[98:113], v[66:69], v[142:145], v[98:113]
	ds_read_b128 v[66:69], v236 offset:288
	ds_read_b128 v[74:77], v236 offset:13088
	v_mfma_f32_32x32x16_bf16 v[114:129], v[70:73], v[142:145], v[114:129]
	s_waitcnt lgkmcnt(0)
	v_mfma_f32_32x32x16_bf16 v[98:113], v[66:69], v[138:141], v[98:113]
	ds_read_b128 v[66:69], v236 offset:320
	ds_read_b128 v[70:73], v236 offset:13120
	v_mfma_f32_32x32x16_bf16 v[114:129], v[74:77], v[138:141], v[114:129]
	s_waitcnt lgkmcnt(0)
	v_mfma_f32_32x32x16_bf16 v[98:113], v[66:69], v[134:137], v[98:113]
	ds_read_b128 v[66:69], v236 offset:352
	ds_read_b128 v[232:235], v236 offset:13152
	v_mfma_f32_32x32x16_bf16 v[114:129], v[70:73], v[134:137], v[114:129]
	s_waitcnt lgkmcnt(0)
	v_mfma_f32_32x32x16_bf16 v[82:97], v[66:69], v[130:133], v[98:113]
	v_mfma_f32_32x32x16_bf16 v[66:81], v[232:235], v[130:133], v[114:129]
	s_mulk_i32 s5, 0x4400
	v_add_u32_e32 v232, s5, v229
	v_add_u32_e32 v250, 0xc800, v232
	v_add_u32_e32 v251, 0xd800, v232
	v_add_u32_e32 v252, 0xe800, v232
	v_add_u32_e32 v253, 0xf800, v232
	s_mulk_i32 s6, 0x4400
	ds_read2_b64 v[98:101], v250 offset1:2
	ds_read2_b64 v[102:105], v251 offset0:32 offset1:34
	ds_read2_b64 v[106:109], v252 offset0:64 offset1:66
	ds_read2_b64 v[110:113], v253 offset0:96 offset1:98
	ds_read2_b64 v[114:117], v250 offset0:4 offset1:6
	ds_read2_b64 v[118:121], v251 offset0:36 offset1:38
	ds_read2_b64 v[122:125], v252 offset0:68 offset1:70
	ds_read2_b64 v[126:129], v253 offset0:100 offset1:102
	v_add_f32_e32 v202, v202, v237
	v_max3_f32 v254, v82, v66, v83
	v_max3_f32 v254, v254, v67, v84
	v_max3_f32 v254, v254, v68, v85
	v_max3_f32 v254, v254, v69, v86
	s_waitcnt lgkmcnt(7)
	v_mfma_f32_32x32x16_bf16 v[50:65], v[98:101], v[186:189], v[50:65]
	ds_read2_b64 v[98:101], v250 offset0:8 offset1:10
	v_max3_f32 v254, v254, v70, v87
	v_max3_f32 v254, v254, v71, v88
	s_waitcnt lgkmcnt(7)
	v_mfma_f32_32x32x16_bf16 v[34:49], v[102:105], v[186:189], v[34:49]
	ds_read2_b64 v[102:105], v251 offset0:40 offset1:42
	v_max3_f32 v254, v254, v72, v89
	v_max3_f32 v254, v254, v73, v90
	s_waitcnt lgkmcnt(7)
	v_mfma_f32_32x32x16_bf16 v[18:33], v[106:109], v[186:189], v[18:33]
	ds_read2_b64 v[106:109], v252 offset0:72 offset1:74
	v_max3_f32 v254, v254, v74, v91
	v_max3_f32 v254, v254, v75, v92
	s_waitcnt lgkmcnt(7)
	v_mfma_f32_32x32x16_bf16 v[2:17], v[110:113], v[186:189], v[2:17]
	ds_read2_b64 v[110:113], v253 offset0:104 offset1:106
	v_max3_f32 v254, v254, v76, v93
	v_max3_f32 v254, v254, v77, v94
	s_waitcnt lgkmcnt(7)
	v_mfma_f32_32x32x16_bf16 v[50:65], v[114:117], v[190:193], v[50:65]
	ds_read2_b64 v[114:117], v250 offset0:12 offset1:14
	v_max3_f32 v254, v254, v78, v95
	v_max3_f32 v254, v254, v79, v96
	s_waitcnt lgkmcnt(7)
	v_mfma_f32_32x32x16_bf16 v[34:49], v[118:121], v[190:193], v[34:49]
	ds_read2_b64 v[118:121], v251 offset0:44 offset1:46
	v_max3_f32 v254, v254, v80, v97
	v_max_f32_e32 v254, v254, v81
	s_waitcnt lgkmcnt(7)
	v_mfma_f32_32x32x16_bf16 v[18:33], v[122:125], v[190:193], v[18:33]
	ds_read2_b64 v[122:125], v252 offset0:76 offset1:78
	v_lshl_add_u64 v[212:213], v[212:213], 0, s[60:61]
	v_lshl_add_u64 v[214:215], v[214:215], 0, s[60:61]
	s_waitcnt lgkmcnt(7)
	v_mfma_f32_32x32x16_bf16 v[2:17], v[126:129], v[190:193], v[2:17]
	ds_read2_b64 v[126:129], v253 offset0:108 offset1:110
	v_lshl_add_u64 v[216:217], v[216:217], 0, s[60:61]
	v_lshl_add_u64 v[218:219], v[218:219], 0, s[60:61]
	v_lshl_add_u64 v[220:221], v[220:221], 0, s[66:67]
	ds_bpermute_b32 v255, v207, v254
	s_waitcnt lgkmcnt(8)
	v_mfma_f32_32x32x16_bf16 v[50:65], v[98:101], v[194:197], v[50:65]
	s_waitcnt lgkmcnt(7)
	v_mfma_f32_32x32x16_bf16 v[34:49], v[102:105], v[194:197], v[34:49]
	s_waitcnt lgkmcnt(6)
	v_mfma_f32_32x32x16_bf16 v[18:33], v[106:109], v[194:197], v[18:33]
	s_waitcnt lgkmcnt(5)
	v_mfma_f32_32x32x16_bf16 v[2:17], v[110:113], v[194:197], v[2:17]
	s_waitcnt lgkmcnt(0)
	v_max_f32_e32 v255, v255, v255
	v_max_f32_e32 v98, v254, v255
	v_add_u32_e32 v255, s6, v231
	v_add_u32_e32 v238, 0xc800, v255
	v_add_u32_e32 v255, 0xea00, v255
	s_cmp_lg_u32 s4, 34
	s_waitcnt vmcnt(0)
	ds_write2_b64 v238, v[178:179], v[180:181] offset1:1
	ds_write2_b64 v255, v[182:183], v[184:185] offset1:1
	s_waitcnt vmcnt(0)
	s_waitcnt lgkmcnt(0)
	s_barrier
	v_mfma_f32_32x32x16_bf16 v[50:65], v[114:117], v[198:201], v[50:65]
	v_mfma_f32_32x32x16_bf16 v[34:49], v[118:121], v[198:201], v[34:49]
	v_mfma_f32_32x32x16_bf16 v[18:33], v[122:125], v[198:201], v[18:33]
	v_mfma_f32_32x32x16_bf16 v[2:17], v[126:129], v[198:201], v[2:17]
	s_cbranch_scc0 .LBB0_819

; #define LAS __attribute__((address_space(3)))
; __device__ __forceinline__ unsigned cvt_pk(float lo, float hi) { unsigned r; asm volatile("v_cvt_pk_bf16_f32 %0, %1, %2" : "=v"(r) : "v"(lo), "v"(hi)); return r; }
; __device__ __forceinline__ void attn_unit(LAS unsigned char* lds, int b, int h, int q0, int kbeg, int ntiles, const bf16_t* Q, const bf16_t* K, const bf16_t* Vt, bf16_t* cat) {
;     ...
;         const LAS unsigned char* kb = lds + (buf ^ 1) * AK_BYTES + r32 * (KP * 2) + hi * 16;
;         f32x16 pn0, pn1;
; #pragma unroll
;         for (int r = 0; r < 16; ++r) { pn0[r] = 0.f; pn1[r] = 0.f; }
;         float ps = 0.f; u32x4 pw[4];
;         bf16x8 ka = *(const LAS bf16x8*)(kb), kbb = *(const LAS bf16x8*)(kb + 32 * (KP * 2));
; #pragma unroll
;         for (int ds = 0; ds < 12; ++ds) {
;             bf16x8 na = ka, nb = kbb;
;             if (ds < 11) { na = *(const LAS bf16x8*)(kb + (ds + 1) * 32); nb = *(const LAS bf16x8*)(kb + 32 * (KP * 2) + (ds + 1) * 32); }
;             pn0 = __builtin_amdgcn_mfma_f32_32x32x16_bf16(ka, qf[ds], pn0, 0, 0, 0);
;             pn1 = __builtin_amdgcn_mfma_f32_32x32x16_bf16(kbb, qf[ds], pn1, 0, 0, 0);
;             if (ds < 8) {
;                 float e[4];
; #pragma unroll
;                 for (int j = 0; j < 4; ++j) { const float v = ds < 4 ? pc0[4 * ds + j] : pc1[4 * (ds - 4) + j]; e[j] = __builtin_amdgcn_exp2f(v - mrun); }
;                 ps += (e[0] + e[1]) + (e[2] + e[3]);
;                 const unsigned w0 = cvt_pk(e[0], e[1]), w1 = cvt_pk(e[2], e[3]);
;                 if ((ds & 1) == 0) { pw[ds >> 1].x = w0; pw[ds >> 1].y = w1; } else { pw[ds >> 1].z = w0; pw[ds >> 1].w = w1; }
;             }
;             ka = na; kbb = nb;
;             __builtin_amdgcn_sched_barrier(0);
;         }
.LBB0_1840:
	s_xor_b32 s6, s5, 1
	s_mul_i32 s7, s6, 0x6400
	v_add_u32_e32 v233, s7, v229
	ds_read_b128 v[98:101], v233
	v_pk_add_f32 v[82:83], v[82:83], v[230:231] op_sel:[0,1] op_sel_hi:[1,1] neg_lo:[0,1] neg_hi:[0,1]
	v_exp_f32_e32 v197, v82
	v_pk_add_f32 v[84:85], v[84:85], v[230:231] op_sel:[0,1] op_sel_hi:[1,1] neg_lo:[0,1] neg_hi:[0,1]
	v_exp_f32_e32 v201, v84
	v_exp_f32_e32 v235, v85
	v_pk_add_f32 v[86:87], v[86:87], v[230:231] op_sel:[0,1] op_sel_hi:[1,1] neg_lo:[0,1] neg_hi:[0,1]
	v_exp_f32_e32 v196, v86
	s_waitcnt lgkmcnt(0)
	v_mfma_f32_32x32x16_bf16 v[98:113], v[98:101], v[174:177], 0
	v_exp_f32_e32 v198, v87
	v_pk_add_f32 v[88:89], v[88:89], v[230:231] op_sel:[0,1] op_sel_hi:[1,1] neg_lo:[0,1] neg_hi:[0,1]
	v_exp_f32_e32 v200, v88
	v_exp_f32_e32 v199, v83
	v_exp_f32_e32 v234, v89
	ds_read_b128 v[188:191], v233 offset:32
	ds_read_b128 v[114:117], v233 offset:12800
	ds_read_b128 v[192:195], v233 offset:12832
	s_add_i32 s4, s4, 1
	v_pk_add_f32 v[82:83], v[196:197], v[198:199]
	v_pk_add_f32 v[84:85], v[200:201], v[234:235]
	s_waitcnt lgkmcnt(0)
	v_mfma_f32_32x32x16_bf16 v[114:129], v[114:117], v[174:177], 0
	v_pk_add_f32 v[236:237], v[82:83], v[84:85] op_sel:[0,0] op_sel_hi:[1,1]
	v_cvt_pk_bf16_f32 v186, v197, v199
	v_cvt_pk_bf16_f32 v187, v201, v235
	v_add_f32_e32 v237, 0, v237
	v_mfma_f32_32x32x16_bf16 v[98:113], v[188:191], v[170:173], v[98:113]
	ds_read_b128 v[82:85], v233 offset:64
	ds_read_b128 v[86:89], v233 offset:12864
	v_add_f32_e32 v197, v236, v237
	v_cvt_pk_bf16_f32 v188, v196, v198
	v_cvt_pk_bf16_f32 v189, v200, v234
	v_mfma_f32_32x32x16_bf16 v[114:129], v[192:195], v[170:173], v[114:129]
	v_pk_add_f32 v[90:91], v[90:91], v[230:231] op_sel:[0,1] op_sel_hi:[1,1] neg_lo:[0,1] neg_hi:[0,1]
	s_waitcnt lgkmcnt(0)
	v_mfma_f32_32x32x16_bf16 v[98:113], v[82:85], v[166:169], v[98:113]
	v_exp_f32_e32 v190, v90
	v_exp_f32_e32 v192, v91
	v_pk_add_f32 v[92:93], v[92:93], v[230:231] op_sel:[0,1] op_sel_hi:[1,1] neg_lo:[0,1] neg_hi:[0,1]
	v_exp_f32_e32 v191, v92
	v_exp_f32_e32 v193, v93
	ds_read_b128 v[82:85], v233 offset:96
	ds_read_b128 v[90:93], v233 offset:12896
	v_mfma_f32_32x32x16_bf16 v[114:129], v[86:89], v[166:169], v[114:129]
	v_pk_add_f32 v[194:195], v[190:191], v[192:193] op_sel:[0,0] op_sel_hi:[1,1]
	v_pk_add_f32 v[198:199], v[194:195], v[194:195] op_sel:[0,0] op_sel_hi:[0,1]
	v_cvt_pk_bf16_f32 v190, v190, v192
	v_cvt_pk_bf16_f32 v191, v191, v193
	v_pk_add_f32 v[94:95], v[94:95], v[230:231] op_sel:[0,1] op_sel_hi:[1,1] neg_lo:[0,1] neg_hi:[0,1]
	s_waitcnt lgkmcnt(0)
	v_mfma_f32_32x32x16_bf16 v[98:113], v[82:85], v[162:165], v[98:113]
	v_exp_f32_e32 v94, v94
	v_exp_f32_e32 v192, v95
	v_pk_add_f32 v[96:97], v[96:97], v[230:231] op_sel:[0,1] op_sel_hi:[1,1] neg_lo:[0,1] neg_hi:[0,1]
	v_exp_f32_e32 v96, v96
	v_exp_f32_e32 v193, v97
	ds_read_b128 v[82:85], v233 offset:128
	ds_read_b128 v[86:89], v233 offset:12928
	v_add_f32_e32 v95, v94, v192
	v_cvt_pk_bf16_f32 v192, v94, v192
	v_add_f32_e32 v97, v96, v193
	v_mfma_f32_32x32x16_bf16 v[114:129], v[90:93], v[162:165], v[114:129]
	v_cvt_pk_bf16_f32 v193, v96, v193
	v_pk_add_f32 v[66:67], v[66:67], v[230:231] op_sel:[0,1] op_sel_hi:[1,1] neg_lo:[0,1] neg_hi:[0,1]
	v_exp_f32_e32 v94, v66
	v_exp_f32_e32 v96, v67
	v_pk_add_f32 v[68:69], v[68:69], v[230:231] op_sel:[0,1] op_sel_hi:[1,1] neg_lo:[0,1] neg_hi:[0,1]
	v_exp_f32_e32 v198, v68
	s_waitcnt lgkmcnt(0)
	v_mfma_f32_32x32x16_bf16 v[98:113], v[82:85], v[158:161], v[98:113]
	v_exp_f32_e32 v196, v69
	ds_read_b128 v[66:69], v233 offset:160
	ds_read_b128 v[82:85], v233 offset:12960
	v_pk_add_f32 v[90:91], v[94:95], v[96:97]
	v_cvt_pk_bf16_f32 v194, v94, v96
	v_pk_add_f32 v[92:93], v[198:199], v[196:197]
	v_cvt_pk_bf16_f32 v195, v198, v196
	v_mfma_f32_32x32x16_bf16 v[114:129], v[86:89], v[158:161], v[114:129]
	v_pk_add_f32 v[90:91], v[90:91], v[92:93] op_sel:[0,0] op_sel_hi:[1,1]
	v_pk_add_f32 v[86:87], v[90:91], v[90:91] op_sel:[0,0] op_sel_hi:[0,1]
	v_pk_add_f32 v[70:71], v[70:71], v[230:231] op_sel:[0,1] op_sel_hi:[1,1] neg_lo:[0,1] neg_hi:[0,1]
	v_exp_f32_e32 v88, v70
	s_waitcnt lgkmcnt(0)
	v_mfma_f32_32x32x16_bf16 v[98:113], v[66:69], v[154:157], v[98:113]
	v_exp_f32_e32 v90, v71
	v_pk_add_f32 v[72:73], v[72:73], v[230:231] op_sel:[0,1] op_sel_hi:[1,1] neg_lo:[0,1] neg_hi:[0,1]
	v_exp_f32_e32 v89, v72
	v_exp_f32_e32 v91, v73
	ds_read_b128 v[66:69], v233 offset:192
	ds_read_b128 v[70:73], v233 offset:12992
	v_cvt_pk_bf16_f32 v196, v88, v90
	v_mfma_f32_32x32x16_bf16 v[114:129], v[82:85], v[154:157], v[114:129]
	v_pk_add_f32 v[92:93], v[88:89], v[90:91] op_sel:[0,0] op_sel_hi:[1,1]
	v_cvt_pk_bf16_f32 v197, v89, v91
	v_pk_add_f32 v[92:93], v[92:93], v[92:93] op_sel_hi:[0,1]
	v_pk_add_f32 v[74:75], v[74:75], v[230:231] op_sel:[0,1] op_sel_hi:[1,1] neg_lo:[0,1] neg_hi:[0,1]
	s_waitcnt lgkmcnt(0)
	v_mfma_f32_32x32x16_bf16 v[98:113], v[66:69], v[150:153], v[98:113]
	v_exp_f32_e32 v82, v74
	v_exp_f32_e32 v84, v75
	v_pk_add_f32 v[76:77], v[76:77], v[230:231] op_sel:[0,1] op_sel_hi:[1,1] neg_lo:[0,1] neg_hi:[0,1]
	v_exp_f32_e32 v86, v76
	v_exp_f32_e32 v88, v77
	ds_read_b128 v[66:69], v233 offset:224
	ds_read_b128 v[74:77], v233 offset:13024
	v_add_f32_e32 v83, v82, v84
	v_cvt_pk_bf16_f32 v198, v82, v84
	v_add_f32_e32 v85, v86, v88
	v_mfma_f32_32x32x16_bf16 v[114:129], v[70:73], v[150:153], v[114:129]
	v_cvt_pk_bf16_f32 v199, v86, v88
	v_pk_add_f32 v[78:79], v[78:79], v[230:231] op_sel:[0,1] op_sel_hi:[1,1] neg_lo:[0,1] neg_hi:[0,1]
	v_exp_f32_e32 v82, v78
	s_waitcnt lgkmcnt(0)
; #define LAS __attribute__((address_space(3)))
; __device__ __forceinline__ unsigned cvt_pk(float lo, float hi) { unsigned r; asm volatile("v_cvt_pk_bf16_f32 %0, %1, %2" : "=v"(r) : "v"(lo), "v"(hi)); return r; }
; __device__ __forceinline__ void attn_unit(LAS unsigned char* lds, int b, int h, int q0, int kbeg, int ntiles, const bf16_t* Q, const bf16_t* K, const bf16_t* Vt, bf16_t* cat) {
;     ...
;         for (int ds = 0; ds < 12; ++ds) {
;             bf16x8 na = ka, nb = kbb;
;             if (ds < 11) { na = *(const LAS bf16x8*)(kb + (ds + 1) * 32); nb = *(const LAS bf16x8*)(kb + 32 * (KP * 2) + (ds + 1) * 32); }
;             pn0 = __builtin_amdgcn_mfma_f32_32x32x16_bf16(ka, qf[ds], pn0, 0, 0, 0);
;             pn1 = __builtin_amdgcn_mfma_f32_32x32x16_bf16(kbb, qf[ds], pn1, 0, 0, 0);
;             if (ds < 8) {
;                 float e[4];
; #pragma unroll
;                 for (int j = 0; j < 4; ++j) { const float v = ds < 4 ? pc0[4 * ds + j] : pc1[4 * (ds - 4) + j]; e[j] = __builtin_amdgcn_exp2f(v - mrun); }
;                 ps += (e[0] + e[1]) + (e[2] + e[3]);
;                 const unsigned w0 = cvt_pk(e[0], e[1]), w1 = cvt_pk(e[2], e[3]);
;                 if ((ds & 1) == 0) { pw[ds >> 1].x = w0; pw[ds >> 1].y = w1; } else { pw[ds >> 1].z = w0; pw[ds >> 1].w = w1; }
;             }
;             ka = na; kbb = nb;
;             __builtin_amdgcn_sched_barrier(0);
;         }
;         lrun += ps;
;         const LAS unsigned char* vb = lds + 2 * AK_BYTES + buf * AV_BYTES + r32 * AV_PITCH + hi * 8;
; #pragma unroll
;         for (int d = 0; d < 4; ++d)
; #pragma unroll
;             for (int ks = 0; ks < 4; ++ks) {
;                 const s16x4 lo = *(const LAS s16x4*)(vb + d * 32 * AV_PITCH + ks * 32), hh = *(const LAS s16x4*)(vb + d * 32 * AV_PITCH + ks * 32 + 16);
;                 const bf16x8 vf = (bf16x8){lo[0], lo[1], lo[2], lo[3], hh[0], hh[1], hh[2], hh[3]};
;                 o[d] = __builtin_amdgcn_mfma_f32_32x32x16_bf16(vf, __builtin_bit_cast(bf16x8, pw[ks]), o[d], 0, 0, 0);
;             }
;         { float mx = fmaxf(pn0[0], pn1[0]);
; #pragma unroll
;           for (int r = 1; r < 16; ++r) mx = fmaxf(mx, fmaxf(pn0[r], pn1[r]));
;           mxc = fmaxf(mx, __shfl_xor(mx, 32)); }
;         if (kt + 1 < ntiles) ASTOREV(buf ^ 1);
;         asm volatile("s_waitcnt vmcnt(0)" ::: "memory");
;         __syncthreads();
	v_mfma_f32_32x32x16_bf16 v[98:113], v[66:69], v[146:149], v[98:113]
	v_exp_f32_e32 v84, v79
	v_pk_add_f32 v[80:81], v[80:81], v[230:231] op_sel:[0,1] op_sel_hi:[1,1] neg_lo:[0,1] neg_hi:[0,1]
	v_exp_f32_e32 v92, v80
	v_exp_f32_e32 v86, v81
	ds_read_b128 v[66:69], v233 offset:256
	ds_read_b128 v[70:73], v233 offset:13056
	v_pk_add_f32 v[78:79], v[82:83], v[84:85]
	v_mfma_f32_32x32x16_bf16 v[114:129], v[74:77], v[146:149], v[114:129]
	v_pk_add_f32 v[80:81], v[92:93], v[86:87] op_sel:[0,0] op_sel_hi:[1,1]
	v_cvt_pk_bf16_f32 v200, v82, v84
	v_cvt_pk_bf16_f32 v201, v92, v86
	v_pk_add_f32 v[78:79], v[78:79], v[80:81] op_sel:[0,0] op_sel_hi:[1,1]
	v_add_f32_e32 v238, v78, v79
	s_waitcnt lgkmcnt(0)
	v_mfma_f32_32x32x16_bf16 v[98:113], v[66:69], v[142:145], v[98:113]
	ds_read_b128 v[66:69], v233 offset:288
	ds_read_b128 v[74:77], v233 offset:13088
	v_mfma_f32_32x32x16_bf16 v[114:129], v[70:73], v[142:145], v[114:129]
	s_waitcnt lgkmcnt(0)
	v_mfma_f32_32x32x16_bf16 v[98:113], v[66:69], v[138:141], v[98:113]
	ds_read_b128 v[66:69], v233 offset:320
	ds_read_b128 v[70:73], v233 offset:13120
	v_mfma_f32_32x32x16_bf16 v[114:129], v[74:77], v[138:141], v[114:129]
	s_waitcnt lgkmcnt(0)
	v_mfma_f32_32x32x16_bf16 v[98:113], v[66:69], v[134:137], v[98:113]
	ds_read_b128 v[66:69], v233 offset:352
	ds_read_b128 v[234:237], v233 offset:13152
	v_mfma_f32_32x32x16_bf16 v[114:129], v[70:73], v[134:137], v[114:129]
	s_waitcnt lgkmcnt(0)
	v_mfma_f32_32x32x16_bf16 v[82:97], v[66:69], v[130:133], v[98:113]
	v_mfma_f32_32x32x16_bf16 v[66:81], v[234:237], v[130:133], v[114:129]
	s_mulk_i32 s5, 0x4400
	v_add_u32_e32 v233, s5, v230
	v_add_u32_e32 v250, 0xc800, v233
	v_add_u32_e32 v251, 0xd800, v233
	v_add_u32_e32 v252, 0xe800, v233
	v_add_u32_e32 v253, 0xf800, v233
	s_mulk_i32 s6, 0x4400
	ds_read2_b64 v[98:101], v250 offset1:2
	ds_read2_b64 v[102:105], v251 offset0:32 offset1:34
	ds_read2_b64 v[106:109], v252 offset0:64 offset1:66
	ds_read2_b64 v[110:113], v253 offset0:96 offset1:98
	ds_read2_b64 v[114:117], v250 offset0:4 offset1:6
	ds_read2_b64 v[118:121], v251 offset0:36 offset1:38
	ds_read2_b64 v[122:125], v252 offset0:68 offset1:70
	ds_read2_b64 v[126:129], v253 offset0:100 offset1:102
	v_add_f32_e32 v202, v202, v238
	v_max3_f32 v254, v82, v66, v83
	v_max3_f32 v254, v254, v67, v84
	v_max3_f32 v254, v254, v68, v85
	v_max3_f32 v254, v254, v69, v86
	s_waitcnt lgkmcnt(7)
	v_mfma_f32_32x32x16_bf16 v[50:65], v[98:101], v[186:189], v[50:65]
	ds_read2_b64 v[98:101], v250 offset0:8 offset1:10
	v_max3_f32 v254, v254, v70, v87
	v_max3_f32 v254, v254, v71, v88
	s_waitcnt lgkmcnt(7)
	v_mfma_f32_32x32x16_bf16 v[34:49], v[102:105], v[186:189], v[34:49]
	ds_read2_b64 v[102:105], v251 offset0:40 offset1:42
	v_max3_f32 v254, v254, v72, v89
	v_max3_f32 v254, v254, v73, v90
	s_waitcnt lgkmcnt(7)
	v_mfma_f32_32x32x16_bf16 v[18:33], v[106:109], v[186:189], v[18:33]
	ds_read2_b64 v[106:109], v252 offset0:72 offset1:74
	v_max3_f32 v254, v254, v74, v91
	v_max3_f32 v254, v254, v75, v92
	s_waitcnt lgkmcnt(7)
	v_mfma_f32_32x32x16_bf16 v[2:17], v[110:113], v[186:189], v[2:17]
	ds_read2_b64 v[110:113], v253 offset0:104 offset1:106
	v_max3_f32 v254, v254, v76, v93
	v_max3_f32 v254, v254, v77, v94
	s_waitcnt lgkmcnt(7)
	v_mfma_f32_32x32x16_bf16 v[50:65], v[114:117], v[190:193], v[50:65]
	ds_read2_b64 v[114:117], v250 offset0:12 offset1:14
	v_max3_f32 v254, v254, v78, v95
	v_max3_f32 v254, v254, v79, v96
	s_waitcnt lgkmcnt(7)
	v_mfma_f32_32x32x16_bf16 v[34:49], v[118:121], v[190:193], v[34:49]
	ds_read2_b64 v[118:121], v251 offset0:44 offset1:46
	v_max3_f32 v254, v254, v80, v97
	v_max_f32_e32 v254, v254, v81
	s_waitcnt lgkmcnt(7)
	v_mfma_f32_32x32x16_bf16 v[18:33], v[122:125], v[190:193], v[18:33]
	ds_read2_b64 v[122:125], v252 offset0:76 offset1:78
	v_lshl_add_u64 v[214:215], v[214:215], 0, s[38:39]
	v_lshl_add_u64 v[216:217], v[216:217], 0, s[38:39]
	s_waitcnt lgkmcnt(7)
	v_mfma_f32_32x32x16_bf16 v[2:17], v[126:129], v[190:193], v[2:17]
	ds_read2_b64 v[126:129], v253 offset0:108 offset1:110
	v_lshl_add_u64 v[218:219], v[218:219], 0, s[38:39]
	v_lshl_add_u64 v[220:221], v[220:221], 0, s[38:39]
	v_lshl_add_u64 v[222:223], v[222:223], 0, s[40:41]
	ds_bpermute_b32 v255, v209, v254
	s_waitcnt lgkmcnt(8)
	v_mfma_f32_32x32x16_bf16 v[50:65], v[98:101], v[194:197], v[50:65]
	s_waitcnt lgkmcnt(7)
	v_mfma_f32_32x32x16_bf16 v[34:49], v[102:105], v[194:197], v[34:49]
	s_waitcnt lgkmcnt(6)
	v_mfma_f32_32x32x16_bf16 v[18:33], v[106:109], v[194:197], v[18:33]
	s_waitcnt lgkmcnt(5)
	v_mfma_f32_32x32x16_bf16 v[2:17], v[110:113], v[194:197], v[2:17]
	s_waitcnt lgkmcnt(0)
	v_max_f32_e32 v255, v255, v255
	v_max_f32_e32 v98, v254, v255
	v_add_u32_e32 v255, s6, v232
	v_add_u32_e32 v239, 0xc800, v255
	v_add_u32_e32 v255, 0xea00, v255
	s_cmp_lg_u32 s4, 34
	s_waitcnt vmcnt(0)
	ds_write2_b64 v239, v[178:179], v[180:181] offset1:1
	ds_write2_b64 v255, v[182:183], v[184:185] offset1:1
	s_waitcnt vmcnt(0)
	s_waitcnt lgkmcnt(0)
	s_barrier
	v_mfma_f32_32x32x16_bf16 v[50:65], v[114:117], v[198:201], v[50:65]
	v_mfma_f32_32x32x16_bf16 v[34:49], v[118:121], v[198:201], v[34:49]
	v_mfma_f32_32x32x16_bf16 v[18:33], v[122:125], v[198:201], v[18:33]
	v_mfma_f32_32x32x16_bf16 v[2:17], v[126:129], v[198:201], v[2:17]
	s_cbranch_scc0 .LBB0_1845
